# diff-attention unit prologue de-serialised (kinf via global load, first K/V tiles requested before the Q wait) + bias pk_fma split into scalar fma
# speedup vs baseline: 1.0146x; 1.0043x over previous
; #define tid (fresh_tid())
; template <int MODE, int DV> ...
;     ...
;     const int q0 = qb * 256, tw0 = q0 + 32 * wid, t = tw0 + r32;
;     const int NT = 4 * qb + 4;
;     bf16x8 qf[4];
;     { const bf16* qp = QK + (rowbase + t) * 2048 + qcol + hi * 8;
; #pragma unroll
;       for (int ds = 0; ds < 4; ++ds) qf[ds] = *(const GAS bf16x8*)(qp + ds * 16); }
;     float rowc = 0.f;
;     if (MODE == 0) {
;         float sa = 0.f, sb2 = 0.f;
; #pragma unroll
;         for (int ds = 0; ds < 4; ++ds) { const u32x4 w = __builtin_bit_cast(u32x4, qf[ds]);
;             const float e0 = __uint_as_float(w.x << 16), e1 = __uint_as_float(w.x & 0xffff0000u), e2 = __uint_as_float(w.y << 16), e3 = __uint_as_float(w.y & 0xffff0000u);
;             const float e4 = __uint_as_float(w.z << 16), e5 = __uint_as_float(w.z & 0xffff0000u), e6 = __uint_as_float(w.w << 16), e7 = __uint_as_float(w.w & 0xffff0000u);
;             const float q2 = (e0 * e0 + e1 * e1) + (e2 * e2 + e3 * e3) + (e4 * e4 + e5 * e5) + (e6 * e6 + e7 * e7);
;             if (ds < 2) sa += q2; else sb2 += q2; }
;         sa = xhalf_sum(sa); sb2 = xhalf_sum(sb2);
;         rowc = (sqrtf(sa * kinfa) + sqrtf(sb2 * kinfb)) * 1.02f;
;     }
;     const int krow = tid >> 3, kch = tid & 7;
;     const bf16* ksrc = QK + (rowbase + krow) * 2048 + kcol + kch * 8;
;     const unsigned kdst = krow * KSTR + kch * 16;
;     const bf16* vsrc = Vt + (size_t)krow * SEQ + kch * 8;
;     const unsigned vdst = KBUFB + krow * KSTR + kch * 16;
;     const unsigned koff = r32 * KSTR + hi * 16;
;     LAS unsigned* flags = (LAS unsigned*)(lds + FLAG_OFF);
;     f32x16 o[NACC];
; #pragma unroll
;     for (int d = 0; d < NACC; ++d)
; #pragma unroll
;         for (int r = 0; r < 16; ++r) o[d][r] = 0.f;
;     float mrun = 0.f, carry = 0.f, lrun = 0.f;
; __global__ void __launch_bounds__(512) fwd_megakernel(Args args) {
;     ...
;                 const int h = 3 - (int)(u >> 5), qb = 31 - (int)(u & 31), b = (int)(xq >> 1), vh = 2 * h + (int)(xq & 1);
;                 const float slope2 = 1.4426950408889634f * exp2f(-2.0f * (float)(h + 1));
;                 const float kinfa = __uint_as_float(kinfw[(b * 8 + vh) * 2]), kinfb = __uint_as_float(kinfw[(b * 8 + vh) * 2 + 1]);
;                 att::attn_unit<0, 128>(lds, QK, vh * 64, 512 + vh * 64, VtD + ((size_t)(b * 512 + h * 128)) * SEQ, (size_t)b * SEQ, qb, slope2, kinfa, kinfb, F, nullptr, vh * 128);
.LBB0_394:
	s_or_b64 exec, exec, s[4:5]
	s_waitcnt lgkmcnt(0)
	s_barrier
	ds_read_b32 v0, v1 offset:55424
	s_mov_b64 s[4:5], -1
	s_waitcnt lgkmcnt(0)
	s_barrier
	v_cmp_lt_u32_e32 vcc, s67, v0
	v_readfirstlane_b32 s6, v0
	s_cbranch_vccnz .LBB0_391
	s_lshr_b32 s3, s6, 5
	s_sub_i32 s8, 3, s3
	s_sub_i32 s3, 4, s3
	v_cvt_f32_ubyte0_e32 v6, s3
	s_lshl_b32 s4, s8, 1
	v_mul_f32_e32 v0, -2.0, v6
	s_andn2_b32 s56, 31, s6
	s_or_b32 s86, s4, s83
	v_cmp_gt_f32_e32 vcc, s77, v0
	s_and_b64 s[4:5], vcc, exec
	s_cselect_b32 s3, 0xffffffc0, 0
	s_lshl_b32 s4, s86, 3
	s_or_b32 s4, s4, s84
	s_add_u32 s4, s45, s4
	s_addc_u32 s5, s64, 0
	v_mov_b64_e32 v[2:3], s[4:5]
	global_load_dwordx2 v[2:3], v[2:3], off
	s_load_dwordx2 s[4:5], s[0:1], 0xc8
	s_load_dwordx2 s[6:7], s[0:1], 0xc8
	v_mov_b32_e32 v8, v156
	s_load_dwordx2 s[38:39], s[0:1], 0xc8
	s_waitcnt lgkmcnt(0)
	s_add_u32 s4, s4, 0xf000000
	s_addc_u32 s5, s5, 0
	s_lshl_b32 s8, s8, 21
	s_or_b32 s8, s8, s85
	s_add_u32 s6, s6, s8
	v_readfirstlane_b32 s8, v8
	s_addc_u32 s7, s7, 0
	s_ashr_i32 s87, s8, 6
	s_lshl_b32 s8, s56, 8
	s_lshl_b32 s88, s87, 5
	v_and_b32_e32 v22, 31, v8
	s_add_i32 s88, s88, s8
	v_or_b32_e32 v140, s88, v22
	v_ashrrev_i32_e32 v141, 31, v140
	v_lshl_add_u64 v[4:5], v[140:141], 0, s[36:37]
	v_lshlrev_b64 v[4:5], 12, v[4:5]
	v_bfe_u32 v23, v8, 5, 1
	v_lshl_add_u64 v[4:5], s[4:5], 0, v[4:5]
	s_lshl_b32 s8, s86, 7
	v_lshl_add_u64 v[4:5], v[4:5], 0, s[8:9]
	v_lshlrev_b32_e32 v0, 4, v23
	v_lshl_add_u64 v[4:5], v[4:5], 0, v[0:1]
	global_load_dwordx4 v[112:115], v[4:5], off
	global_load_dwordx4 v[116:119], v[4:5], off offset:32
	global_load_dwordx4 v[120:123], v[4:5], off offset:64
	global_load_dwordx4 v[124:127], v[4:5], off offset:96
	v_cndmask_b32_e32 v7, 0, v158, vcc
	v_fmac_f32_e32 v7, -2.0, v6
	v_exp_f32_e32 v4, v7
	v_and_b32_e32 v141, 63, v8
	v_and_b32_e32 v24, 7, v8
	v_lshlrev_b32_e32 v144, 4, v24
	v_ldexp_f32 v4, v4, s3
	v_mul_f32_e32 v142, 0x3fb8aa3b, v4
	v_ashrrev_i32_e32 v4, 3, v8
	s_lshl_b32 s3, s56, 2
	s_or_b32 s89, s3, 3
	s_or_b32 s3, s3, 2
	v_lshlrev_b32_e32 v160, 3, v23
	v_lshlrev_b32_e32 v150, 3, v24
	v_mad_u32_u24 v163, v22, s79, v0
	v_lshl_add_u32 v164, v24, 2, 0
	v_lshlrev_b32_e32 v165, 2, v23
	v_mov_b32_e32 v0, v1
	s_or_b32 s91, s88, 31
	v_sub_u32_e32 v166, v165, v140
	v_add_u32_e32 v167, 1, v140
	v_mov_b32_e32 v152, v142
	v_mov_b32_e32 v153, v142
	v_mov_b32_e32 v154, v142
	v_mov_b32_e32 v155, v142
	v_mov_b32_e32 v168, 0
	s_mov_b64 s[58:59], 0
	v_mov_b32_e32 v208, v4
	v_ashrrev_i32_e32 v209, 31, v4
	v_lshlrev_b64 v[210:211], 14, v[208:209]
	v_lshl_add_u64 v[210:211], s[6:7], 0, v[210:211]
	v_mad_u64_u32 v[212:213], s[6:7], v4, s79, v[144:145]
	v_lshl_add_u64 v[214:215], v[208:209], 0, s[36:37]
	v_lshlrev_b64 v[214:215], 12, v[214:215]
	v_lshl_add_u64 v[216:217], s[4:5], 0, v[214:215]
	v_lshl_add_u64 v[216:217], v[216:217], 0, s[8:9]
	v_mov_b32_e32 v145, v1
	v_lshl_add_u64 v[146:147], v[216:217], 0, v[144:145]
	v_lshl_add_u64 v[216:217], v[210:211], 0, v[144:145]
	s_lshl_b32 s8, s89, 18
	v_lshl_add_u64 v[148:149], v[216:217], 0, s[10:11]
	v_lshl_add_u64 v[218:219], v[146:147], 0, s[8:9]
	s_lshl_b32 s8, s89, 7
	v_lshl_add_u64 v[220:221], v[148:149], 0, s[8:9]
	v_add_co_u32_e32 v222, vcc, s80, v220
	s_nop 1
	v_addc_co_u32_e32 v223, vcc, 0, v221, vcc
	s_lshl_b32 s8, s3, 18
	global_load_dwordx4 v[196:199], v[218:219], off offset:1024
	global_load_dwordx4 v[200:203], v[220:221], off
	global_load_dwordx4 v[204:207], v[222:223], off
	v_lshl_add_u64 v[224:225], v[146:147], 0, s[8:9]
	s_lshl_b32 s8, s3, 7
	global_load_dwordx4 v[128:131], v[224:225], off offset:1024
	v_lshl_add_u64 v[226:227], v[148:149], 0, s[8:9]
	v_add_co_u32_e32 v228, vcc, s80, v226
	s_nop 1
	v_addc_co_u32_e32 v229, vcc, 0, v227, vcc
	global_load_dwordx4 v[132:135], v[226:227], off
	global_load_dwordx4 v[136:139], v[228:229], off
	s_waitcnt vmcnt(6)
; template <int MODE, int DV> ...
;     ...
;     float rowc = 0.f;
;     if (MODE == 0) {
;         float sa = 0.f, sb2 = 0.f;
; #pragma unroll
;         for (int ds = 0; ds < 4; ++ds) { const u32x4 w = __builtin_bit_cast(u32x4, qf[ds]);
;             const float e0 = __uint_as_float(w.x << 16), e1 = __uint_as_float(w.x & 0xffff0000u), e2 = __uint_as_float(w.y << 16), e3 = __uint_as_float(w.y & 0xffff0000u);
;             const float e4 = __uint_as_float(w.z << 16), e5 = __uint_as_float(w.z & 0xffff0000u), e6 = __uint_as_float(w.w << 16), e7 = __uint_as_float(w.w & 0xffff0000u);
;             const float q2 = (e0 * e0 + e1 * e1) + (e2 * e2 + e3 * e3) + (e4 * e4 + e5 * e5) + (e6 * e6 + e7 * e7);
;             if (ds < 2) sa += q2; else sb2 += q2; }
;         sa = xhalf_sum(sa); sb2 = xhalf_sum(sb2);
;         rowc = (sqrtf(sa * kinfa) + sqrtf(sb2 * kinfb)) * 1.02f;
;     }
;     const int krow = tid >> 3, kch = tid & 7;
;     const bf16* ksrc = QK + (rowbase + krow) * 2048 + kcol + kch * 8;
;     const unsigned kdst = krow * KSTR + kch * 16;
;     const bf16* vsrc = Vt + (size_t)krow * SEQ + kch * 8;
;     const unsigned vdst = KBUFB + krow * KSTR + kch * 16;
;     const unsigned koff = r32 * KSTR + hi * 16;
;     LAS unsigned* flags = (LAS unsigned*)(lds + FLAG_OFF);
;     f32x16 o[NACC];
; #pragma unroll
;     for (int d = 0; d < NACC; ++d)
; #pragma unroll
;         for (int r = 0; r < 16; ++r) o[d][r] = 0.f;
;     float mrun = 0.f, carry = 0.f, lrun = 0.f;
;     bool wdone = false, first = true;
;     bf16x8 ut0, ut1, uone;
;     { const u32x4 c = {0x3F803F80u, 0x3F803F80u, 0x3F803F80u, 0x3F803F80u}; uone = __builtin_bit_cast(bf16x8, c); }
;     if (MODE == 1) {
;         u32x4 a, b;
;         unsigned e0[8], e1[8];
; #pragma unroll
;         for (int j = 0; j < 8; ++j) { const int jj = 8 * (j >> 2) + 4 * hi + (j & 3); e0[j] = (jj > r32) ? 0x3F80u : 0u; e1[j] = (16 + jj > r32) ? 0x3F80u : 0u; }
;         a.x = e0[0] | (e0[1] << 16); a.y = e0[2] | (e0[3] << 16); a.z = e0[4] | (e0[5] << 16); a.w = e0[6] | (e0[7] << 16);
;         b.x = e1[0] | (e1[1] << 16); b.y = e1[2] | (e1[3] << 16); b.z = e1[4] | (e1[5] << 16); b.w = e1[6] | (e1[7] << 16);
;         ut0 = __builtin_bit_cast(bf16x8, a); ut1 = __builtin_bit_cast(bf16x8, b);
;     }
;     u32x4 kreg[2], vreg[2][NVC];
;     ...
;     ATT_LOAD(0, NT - 1); ATT_LOAD(1, (NT - 2 > 0) ? NT - 2 : 0); ATT_STORE(0, 0);
	v_and_b32_e32 v6, 0xffff0000, v112
	v_and_b32_e32 v8, 0xffff0000, v113
	v_and_b32_e32 v14, 0xffff0000, v116
	v_and_b32_e32 v16, 0xffff0000, v117
	v_lshlrev_b32_e32 v5, 16, v112
	v_lshlrev_b32_e32 v7, 16, v113
	v_and_b32_e32 v10, 0xffff0000, v114
	v_lshlrev_b32_e32 v13, 16, v116
	v_lshlrev_b32_e32 v15, 16, v117
	v_and_b32_e32 v18, 0xffff0000, v118
	v_mul_f32_e32 v6, v6, v6
	v_mul_f32_e32 v8, v8, v8
	v_mul_f32_e32 v14, v14, v14
	v_mul_f32_e32 v16, v16, v16
	v_lshlrev_b32_e32 v9, 16, v114
	v_and_b32_e32 v12, 0xffff0000, v115
	v_lshlrev_b32_e32 v17, 16, v118
	v_and_b32_e32 v20, 0xffff0000, v119
	v_mul_f32_e32 v10, v10, v10
	v_mul_f32_e32 v18, v18, v18
	v_fmac_f32_e32 v6, v5, v5
	v_fmac_f32_e32 v8, v7, v7
	v_fmac_f32_e32 v14, v13, v13
	v_fmac_f32_e32 v16, v15, v15
	v_lshlrev_b32_e32 v11, 16, v115
	v_lshlrev_b32_e32 v19, 16, v119
	v_mul_f32_e32 v12, v12, v12
	v_mul_f32_e32 v20, v20, v20
	v_fmac_f32_e32 v10, v9, v9
	v_fmac_f32_e32 v18, v17, v17
	v_add_f32_e32 v5, v6, v8
	v_add_f32_e32 v6, v14, v16
	v_fmac_f32_e32 v12, v11, v11
	v_fmac_f32_e32 v20, v19, v19
	v_add_f32_e32 v5, v10, v5
	v_add_f32_e32 v6, v18, v6
	v_add_f32_e32 v5, v12, v5
	v_add_f32_e32 v6, v20, v6
	v_and_b32_e32 v25, 0xffff0000, v120
	v_and_b32_e32 v27, 0xffff0000, v121
	v_add_f32_e32 v19, v5, v6
	s_nop 0
	v_lshlrev_b32_e32 v21, 16, v120
	v_lshlrev_b32_e32 v26, 16, v121
	v_and_b32_e32 v29, 0xffff0000, v122
	v_mul_f32_e32 v25, v25, v25
	v_mul_f32_e32 v27, v27, v27
	s_nop 0
	v_lshlrev_b32_e32 v28, 16, v122
	v_and_b32_e32 v31, 0xffff0000, v123
	v_and_b32_e32 v33, 0xffff0000, v124
	v_mul_f32_e32 v29, v29, v29
	v_fmac_f32_e32 v25, v21, v21
	v_fmac_f32_e32 v27, v26, v26
	s_nop 0
	s_nop 0
	v_and_b32_e32 v20, 0xffff0000, v125
	v_lshlrev_b32_e32 v30, 16, v123
	v_lshlrev_b32_e32 v32, 16, v124
	v_mul_f32_e32 v31, v31, v31
	v_fmac_f32_e32 v29, v28, v28
	v_add_f32_e32 v7, v25, v27
	v_lshlrev_b32_e32 v17, 16, v125
	v_mul_f32_e32 v28, v33, v33
	v_mul_f32_e32 v20, v20, v20
	v_fmac_f32_e32 v31, v30, v30
	v_add_f32_e32 v7, v29, v7
	v_and_b32_e32 v25, 0xffff0000, v126
	v_fmac_f32_e32 v28, v32, v32
	v_fmac_f32_e32 v20, v17, v17
	v_add_f32_e32 v18, v31, v7
	s_nop 0
	v_lshlrev_b32_e32 v21, 16, v126
	v_add_f32_e32 v17, v28, v20
	v_mul_f32_e32 v20, v25, v25
	s_nop 0
	v_and_b32_e32 v27, 0xffff0000, v127
	v_fmac_f32_e32 v20, v21, v21
	s_nop 0
	v_lshlrev_b32_e32 v26, 16, v127
	v_add_f32_e32 v17, v20, v17
	v_mul_f32_e32 v20, v27, v27
	s_nop 0
	s_nop 0
	v_fmac_f32_e32 v20, v26, v26
	s_nop 0
	s_nop 0
	s_nop 0
	v_add_f32_e32 v17, v20, v17
	s_nop 0
	s_nop 0
	s_nop 0
	v_add_f32_e32 v17, v18, v17
	v_mov_b32_e32 v18, v19
	s_nop 0
	s_nop 0
	v_permlane32_swap_b32_e32 v19, v18
	s_nop 0
	v_add_f32_e32 v18, v19, v18
	s_nop 0
	s_nop 0
	v_mul_f32_e32 v2, v2, v18
	v_mul_f32_e32 v18, 0x4f800000, v2
	v_cmp_gt_f32_e32 vcc, s78, v2
	s_nop 0
	s_nop 0
	s_nop 0
	v_cndmask_b32_e32 v2, v2, v18, vcc
	s_nop 0
	s_nop 0
	s_nop 0
	s_nop 0
	v_sqrt_f32_e32 v26, v2
	s_nop 0
	s_nop 0
	v_add_u32_e32 v18, -1, v26
	v_mov_b32_e32 v25, v17
	v_fma_f32 v19, -v18, v26, v2
	s_nop 0
	v_permlane32_swap_b32_e32 v17, v25
	v_cmp_ge_f32_e64 s[4:5], 0, v19
	v_add_u32_e32 v19, 1, v26
	v_add_f32_e32 v17, v17, v25
	v_fma_f32 v20, -v19, v26, v2
	v_cndmask_b32_e64 v18, v26, v18, s[4:5]
	v_cmp_lt_f32_e64 s[4:5], 0, v20
	v_mul_f32_e32 v3, v3, v17
	v_mul_f32_e32 v17, 0x4f800000, v3
	v_cndmask_b32_e64 v18, v18, v19, s[4:5]
	v_cmp_gt_f32_e64 s[4:5], s78, v3
	v_mul_f32_e32 v19, 0x37800000, v18
	v_cndmask_b32_e32 v18, v18, v19, vcc
	v_cndmask_b32_e64 v3, v3, v17, s[4:5]
	v_sqrt_f32_e32 v17, v3
	v_cmp_class_f32_e32 vcc, v2, v157
	v_add_u32_e32 v162, 0, v212
	s_waitcnt vmcnt(5)
	ds_write_b128 v162, v[196:199]
	s_waitcnt vmcnt(4)
	ds_write_b128 v162, v[200:203] offset:9216
	s_waitcnt vmcnt(3)
	ds_write_b128 v162, v[204:207] offset:18432
	v_cndmask_b32_e32 v2, v18, v2, vcc
	v_add_u32_e32 v18, -1, v17
	v_fma_f32 v19, -v18, v17, v3
	v_cmp_ge_f32_e32 vcc, 0, v19
	v_add_u32_e32 v19, 1, v17
	v_mov_b32_e32 v14, v1
	v_cndmask_b32_e32 v18, v17, v18, vcc
	v_fma_f32 v17, -v19, v17, v3
	v_cmp_lt_f32_e32 vcc, 0, v17
	v_mov_b32_e32 v15, v1
	v_mul_u32_u24_e32 v145, 0x90, v22
	v_cndmask_b32_e32 v17, v18, v19, vcc
	v_mul_f32_e32 v18, 0x37800000, v17
	v_cndmask_b32_e64 v17, v17, v18, s[4:5]
	v_cmp_class_f32_e32 vcc, v3, v157
	s_lshl_b32 s3, s87, 2
	v_mov_b32_e32 v4, v1
	v_cndmask_b32_e32 v3, v17, v3, vcc
	v_add_f32_e32 v2, v2, v3
	v_mul_f32_e32 v161, 0x3f828f5c, v2
	v_mov_b32_e32 v2, v1
	v_mov_b32_e32 v3, v1
	v_mov_b32_e32 v5, v1
	v_mov_b32_e32 v6, v1
	v_mov_b32_e32 v7, v1
	v_mov_b32_e32 v8, v1
	v_mov_b32_e32 v9, v1
	v_mov_b32_e32 v10, v1
	v_mov_b32_e32 v11, v1
	v_mov_b32_e32 v12, v1
	v_mov_b32_e32 v13, v1
	v_mov_b64_e32 v[30:31], v[14:15]
	v_mov_b64_e32 v[46:47], v[14:15]
	v_mov_b64_e32 v[62:63], v[14:15]
	v_mov_b64_e32 v[78:79], v[14:15]
	s_add_i32 s90, s3, 0
	v_cmp_eq_u32_e64 s[4:5], 0, v141
	s_mov_b64 s[6:7], -1
	v_mov_b64_e32 v[28:29], v[12:13]
	v_mov_b64_e32 v[26:27], v[10:11]
	v_mov_b64_e32 v[24:25], v[8:9]
	v_mov_b64_e32 v[22:23], v[6:7]
	v_mov_b64_e32 v[20:21], v[4:5]
	v_mov_b64_e32 v[18:19], v[2:3]
	v_mov_b64_e32 v[16:17], v[0:1]
	v_mov_b64_e32 v[44:45], v[12:13]
	v_mov_b64_e32 v[42:43], v[10:11]
	v_mov_b64_e32 v[40:41], v[8:9]
	v_mov_b64_e32 v[38:39], v[6:7]
	v_mov_b64_e32 v[36:37], v[4:5]
	v_mov_b64_e32 v[34:35], v[2:3]
	v_mov_b64_e32 v[32:33], v[0:1]
	v_mov_b64_e32 v[60:61], v[12:13]
	v_mov_b64_e32 v[58:59], v[10:11]
	v_mov_b64_e32 v[56:57], v[8:9]
	v_mov_b64_e32 v[54:55], v[6:7]
	v_mov_b64_e32 v[52:53], v[4:5]
	v_mov_b64_e32 v[50:51], v[2:3]
	v_mov_b64_e32 v[48:49], v[0:1]
	v_mov_b64_e32 v[76:77], v[12:13]
	v_mov_b64_e32 v[74:75], v[10:11]
	v_mov_b64_e32 v[72:73], v[8:9]
	v_mov_b64_e32 v[70:71], v[6:7]
	v_mov_b64_e32 v[68:69], v[4:5]
	v_mov_b64_e32 v[66:67], v[2:3]
	v_mov_b64_e32 v[64:65], v[0:1]
	v_mov_b32_e32 v14, 0
	s_waitcnt lgkmcnt(0)
	s_barrier
	s_branch .LBB0_399

; #define LAS __attribute__((address_space(3)))
; __device__ __forceinline__ int crow(int r, int hi) { return (r & 3) + 8 * (r >> 2) + 4 * hi; }
; #define MFMA32(a, b, c) __builtin_amdgcn_mfma_f32_32x32x16_bf16((a), (b), (c), 0, 0, 0)
; #define ATT_LOAD(set_, kt_) do { kreg[set_] = *(const GAS u32x4*)(ksrc + (size_t)(kt_) * 64 * 2048); \
;         _Pragma("unroll") for (int i_ = 0; i_ < NVC; ++i_) vreg[set_][i_] = *(const GAS u32x4*)(vsrc + (size_t)i_ * 64 * SEQ + (kt_) * 64); } while (0)
; #define ATT_LOAD(set_, kt_) do { _Pragma("unroll") for (int i_ = 0; i_ < 2; ++i_) { kreg[set_][i_] = *(const GAS u32x4*)(ksrc + ((size_t)(kt_) * 64 + 32 * i_) * 2048); \
;         vreg[set_][i_] = *(const GAS u32x4*)(vsrc + (size_t)i_ * 32 * SEQ + (kt_) * 64); } } while (0)
; template <int MODE, int DV> ...
;     ...
;       for (int hh = 0; hh < 2; ++hh) {
;         const bool hasn = (kt > 0);
;         ATT_LOAD(hh, (kt - 2 > 0) ? kt - 2 : 0);
;         const int k0 = kt * 64;
;         const LAS unsigned char* sb = lds + hh * STAGEB;
;         const bool active = ((MODE == 0) ? (k0 <= tw0 + 31) : (k0 < tw0 + 31)) && !wdone;
;         if (active) {
;             f32x16 p0, p1;
;             if (MODE == 0) {
;                 const float bb = slope2 * (float)(k0 + 4 * hi - t) - mrun;
; #pragma unroll
;                 for (int r = 0; r < 16; ++r) { const float c = __builtin_fmaf(slope2, (float)((r & 3) + 8 * (r >> 2)), bb); p0[r] = c; p1[r] = __builtin_fmaf(slope2, 32.0f, c); }
;             } else {
; #pragma unroll
;                 for (int r = 0; r < 16; ++r) { p0[r] = 0.f; p1[r] = 0.f; }
;             }
; #pragma unroll
;             for (int ds = 0; ds < 4; ++ds) {
;                 const bf16x8 k0f = *(const LAS bf16x8*)(sb + koff + ds * 32);
;                 const bf16x8 k1f = *(const LAS bf16x8*)(sb + koff + 32 * KSTR + ds * 32);
;                 p0 = MFMA32(k0f, qf[ds], p0); p1 = MFMA32(k1f, qf[ds], p1);
;             }
;             const bool diag = (MODE == 0) ? (k0 + 63 > tw0) : (k0 + 63 >= tw0);
;             bf16x8 pf0, pf1, pf2, pf3;
;             if (MODE == 0) {
;                 if (diag) {
; #pragma unroll
;                     for (int r = 0; r < 16; ++r) { const int key = k0 + crow(r, hi); if (key > t) p0[r] = -INFINITY; if (key + 32 > t) p1[r] = -INFINITY; }
;                 }
.Lst_skip0:
	v_add_co_u32_e32 v10, vcc, 0x100000, v6
	v_lshl_add_u64 v[2:3], v[146:147], 0, s[48:49]
	s_nop 0
	v_addc_co_u32_e32 v11, vcc, 0, v7, vcc
	global_load_dwordx4 v[2:5], v[2:3], off offset:1024
	s_nop 0
	global_load_dwordx4 v[6:9], v[6:7], off
	s_nop 0
	global_load_dwordx4 v[10:13], v[10:11], off
	s_lshl_b32 s8, s89, 6
	s_cmp_gt_i32 s8, s91
	s_cselect_b64 s[48:49], -1, 0
	s_or_b64 s[48:49], s[48:49], s[58:59]
	s_and_b64 vcc, exec, s[48:49]
	s_cbranch_vccnz .LBB0_410
	v_add_u32_e32 v0, s8, v166
	v_cvt_f32_i32_e32 v0, v0
	v_mov_b32_e32 v143, v142
	s_or_b32 s3, s8, 63
	s_cmp_le_i32 s3, s88
	v_fma_f32 v0, v142, v0, -v14
	v_fma_f32 v80, 0, v142, v0
	v_add_f32_e32 v81, v142, v0
	v_fma_f32 v82, v152, s12, v0
	v_fma_f32 v83, v153, s13, v0
	v_fma_f32 v84, v152, s14, v0
	v_fma_f32 v85, v153, s15, v0
	v_fma_f32 v86, v152, s16, v0
	v_fma_f32 v87, v153, s17, v0
	v_fma_f32 v88, v152, s18, v0
	v_fma_f32 v89, v153, s19, v0
	v_fma_f32 v90, v152, s20, v0
	v_fma_f32 v91, v153, s21, v0
	v_fma_f32 v92, v152, s22, v0
	v_fma_f32 v93, v153, s23, v0
	v_fma_f32 v94, v152, s24, v0
	v_fma_f32 v95, v153, s25, v0
	v_add_u32_e32 v0, 0, v163
	ds_read_b128 v[170:173], v0
	ds_read_b128 v[174:177], v0 offset:32
	v_fma_f32 v110, v142, s28, v94
	v_fma_f32 v111, v143, s28, v95
	v_fma_f32 v108, v142, s28, v92
	v_fma_f32 v109, v143, s28, v93
	v_fma_f32 v106, v142, s28, v90
	v_fma_f32 v107, v143, s28, v91
	v_fma_f32 v104, v142, s28, v88
	v_fma_f32 v105, v143, s28, v89
	v_fma_f32 v102, v142, s28, v86
	v_fma_f32 v103, v143, s28, v87
	v_fma_f32 v100, v142, s28, v84
	v_fma_f32 v101, v143, s28, v85
	v_fma_f32 v98, v142, s28, v82
	v_fma_f32 v99, v143, s28, v83
	v_fma_f32 v96, v154, s28, v80
	v_fma_f32 v97, v155, s28, v81
	s_waitcnt lgkmcnt(1)
	v_mfma_f32_32x32x16_bf16 v[80:95], v[170:173], v[112:115], v[80:95]
	ds_read_b128 v[170:173], v0 offset:4608
	ds_read_b128 v[178:181], v0 offset:4640
	s_waitcnt lgkmcnt(1)
	v_mfma_f32_32x32x16_bf16 v[96:111], v[170:173], v[112:115], v[96:111]
	v_mfma_f32_32x32x16_bf16 v[80:95], v[174:177], v[116:119], v[80:95]
	ds_read_b128 v[170:173], v0 offset:64
	ds_read_b128 v[174:177], v0 offset:96
	s_waitcnt lgkmcnt(2)
	v_mfma_f32_32x32x16_bf16 v[96:111], v[178:181], v[116:119], v[96:111]
	s_waitcnt lgkmcnt(1)
	v_mfma_f32_32x32x16_bf16 v[80:95], v[170:173], v[120:123], v[80:95]
	ds_read_b128 v[170:173], v0 offset:4672
	ds_read_b128 v[178:181], v0 offset:4704
	s_waitcnt lgkmcnt(1)
	v_mfma_f32_32x32x16_bf16 v[96:111], v[170:173], v[120:123], v[96:111]
	v_mfma_f32_32x32x16_bf16 v[80:95], v[174:177], v[124:127], v[80:95]
	s_waitcnt lgkmcnt(0)
	v_mfma_f32_32x32x16_bf16 v[96:111], v[178:181], v[124:127], v[96:111]
	s_cbranch_scc1 .LBB0_402
	v_or_b32_e32 v15, s8, v165
	v_or_b32_e32 v143, 32, v15
	v_cmp_le_i32_e32 vcc, v143, v140
	v_or_b32_e32 v143, 33, v15
	s_nop 6
	v_cndmask_b32_e32 v96, v159, v96, vcc
	v_cmp_lt_i32_e32 vcc, v15, v140
	s_nop 1
	v_cndmask_b32_e32 v81, v159, v81, vcc
	v_cmp_le_i32_e32 vcc, v15, v140
	s_nop 1
	v_cndmask_b32_e32 v80, v159, v80, vcc
	v_cmp_le_i32_e32 vcc, v143, v140
	v_or_b32_e32 v143, 2, v15
	s_nop 0
	v_cndmask_b32_e32 v97, v159, v97, vcc
	v_cmp_le_i32_e32 vcc, v143, v140
	v_or_b32_e32 v143, 34, v15
	s_nop 0
	v_cndmask_b32_e32 v82, v159, v82, vcc
	v_cmp_le_i32_e32 vcc, v143, v140
	v_or_b32_e32 v143, 3, v15
	s_nop 0
	v_cndmask_b32_e32 v98, v159, v98, vcc
	v_cmp_le_i32_e32 vcc, v143, v140
	v_or_b32_e32 v143, 35, v15
	s_nop 0
	v_cndmask_b32_e32 v83, v159, v83, vcc
	v_cmp_le_i32_e32 vcc, v143, v140
	v_or_b32_e32 v143, 8, v15
	s_nop 0
	v_cndmask_b32_e32 v99, v159, v99, vcc
	v_cmp_le_i32_e32 vcc, v143, v140
	v_or_b32_e32 v143, 40, v15
	s_nop 0
	v_cndmask_b32_e32 v84, v159, v84, vcc
	v_cmp_le_i32_e32 vcc, v143, v140
	v_or_b32_e32 v143, 9, v15
	s_nop 0
	v_cndmask_b32_e32 v100, v159, v100, vcc
	v_cmp_le_i32_e32 vcc, v143, v140
	v_or_b32_e32 v143, 41, v15
	s_nop 0
	v_cndmask_b32_e32 v85, v159, v85, vcc
	v_cmp_le_i32_e32 vcc, v143, v140
	v_or_b32_e32 v143, 10, v15
	s_nop 0
	v_cndmask_b32_e32 v101, v159, v101, vcc
	v_cmp_le_i32_e32 vcc, v143, v140
	v_or_b32_e32 v143, 42, v15
	s_nop 0
	v_cndmask_b32_e32 v86, v159, v86, vcc
	v_cmp_le_i32_e32 vcc, v143, v140
	v_or_b32_e32 v143, 11, v15
	s_nop 0
	v_cndmask_b32_e32 v102, v159, v102, vcc
	v_cmp_le_i32_e32 vcc, v143, v140
	v_or_b32_e32 v143, 43, v15
	s_nop 0
	v_cndmask_b32_e32 v87, v159, v87, vcc
	v_cmp_le_i32_e32 vcc, v143, v140
	v_or_b32_e32 v143, 16, v15
	s_nop 0
	v_cndmask_b32_e32 v103, v159, v103, vcc
	v_cmp_le_i32_e32 vcc, v143, v140
	v_or_b32_e32 v143, 48, v15
	s_nop 0
	v_cndmask_b32_e32 v88, v159, v88, vcc
	v_cmp_le_i32_e32 vcc, v143, v140
	v_or_b32_e32 v143, 17, v15
	s_nop 0
	v_cndmask_b32_e32 v104, v159, v104, vcc
	v_cmp_le_i32_e32 vcc, v143, v140
	v_or_b32_e32 v143, 49, v15
	s_nop 0
	v_cndmask_b32_e32 v89, v159, v89, vcc
	v_cmp_le_i32_e32 vcc, v143, v140
	v_or_b32_e32 v143, 18, v15
	s_nop 0
	v_cndmask_b32_e32 v105, v159, v105, vcc
	v_cmp_le_i32_e32 vcc, v143, v140
	v_or_b32_e32 v143, 50, v15
	s_nop 0
	v_cndmask_b32_e32 v90, v159, v90, vcc
	v_cmp_le_i32_e32 vcc, v143, v140
	v_or_b32_e32 v143, 19, v15
	s_nop 0
	v_cndmask_b32_e32 v106, v159, v106, vcc
	v_cmp_le_i32_e32 vcc, v143, v140
	v_or_b32_e32 v143, 51, v15
	s_nop 0
	v_cndmask_b32_e32 v91, v159, v91, vcc
	v_cmp_le_i32_e32 vcc, v143, v140
	v_or_b32_e32 v143, 24, v15
	s_nop 0
	v_cndmask_b32_e32 v107, v159, v107, vcc
	v_cmp_le_i32_e32 vcc, v143, v140
	v_or_b32_e32 v143, 56, v15
	s_nop 0
	v_cndmask_b32_e32 v92, v159, v92, vcc
	v_cmp_le_i32_e32 vcc, v143, v140
	v_or_b32_e32 v143, 25, v15
	s_nop 0
	v_cndmask_b32_e32 v108, v159, v108, vcc
	v_cmp_le_i32_e32 vcc, v143, v140
	v_or_b32_e32 v143, 57, v15
	s_nop 0
	v_cndmask_b32_e32 v93, v159, v93, vcc
	v_cmp_le_i32_e32 vcc, v143, v140
	v_or_b32_e32 v143, 26, v15
	s_nop 0
	v_cndmask_b32_e32 v109, v159, v109, vcc
	v_cmp_le_i32_e32 vcc, v143, v140
	v_or_b32_e32 v143, 58, v15
	s_nop 0
	v_cndmask_b32_e32 v94, v159, v94, vcc
	v_cmp_le_i32_e32 vcc, v143, v140
	v_or_b32_e32 v143, 27, v15
	v_or_b32_e32 v15, 59, v15
	v_cndmask_b32_e32 v110, v159, v110, vcc
	v_cmp_le_i32_e32 vcc, v143, v140
	s_nop 1
	v_cndmask_b32_e32 v95, v159, v95, vcc
	v_cmp_le_i32_e32 vcc, v15, v140
	s_nop 1
	v_cndmask_b32_e32 v111, v159, v111, vcc

; #define LAS __attribute__((address_space(3)))
; __device__ __forceinline__ int crow(int r, int hi) { return (r & 3) + 8 * (r >> 2) + 4 * hi; }
; #define MFMA32(a, b, c) __builtin_amdgcn_mfma_f32_32x32x16_bf16((a), (b), (c), 0, 0, 0)
; #define ATT_LOAD(set_, kt_) do { kreg[set_] = *(const GAS u32x4*)(ksrc + (size_t)(kt_) * 64 * 2048); \
;         _Pragma("unroll") for (int i_ = 0; i_ < NVC; ++i_) vreg[set_][i_] = *(const GAS u32x4*)(vsrc + (size_t)i_ * 64 * SEQ + (kt_) * 64); } while (0)
; #define ATT_LOAD(set_, kt_) do { _Pragma("unroll") for (int i_ = 0; i_ < 2; ++i_) { kreg[set_][i_] = *(const GAS u32x4*)(ksrc + ((size_t)(kt_) * 64 + 32 * i_) * 2048); \
;         vreg[set_][i_] = *(const GAS u32x4*)(vsrc + (size_t)i_ * 32 * SEQ + (kt_) * 64); } } while (0)
; template <int MODE, int DV> ...
;     ...
;       for (int hh = 0; hh < 2; ++hh) {
;         const bool hasn = (kt > 0);
;         ATT_LOAD(hh, (kt - 2 > 0) ? kt - 2 : 0);
;         const int k0 = kt * 64;
;         const LAS unsigned char* sb = lds + hh * STAGEB;
;         const bool active = ((MODE == 0) ? (k0 <= tw0 + 31) : (k0 < tw0 + 31)) && !wdone;
;         if (active) {
;             f32x16 p0, p1;
;             if (MODE == 0) {
;                 const float bb = slope2 * (float)(k0 + 4 * hi - t) - mrun;
; #pragma unroll
;                 for (int r = 0; r < 16; ++r) { const float c = __builtin_fmaf(slope2, (float)((r & 3) + 8 * (r >> 2)), bb); p0[r] = c; p1[r] = __builtin_fmaf(slope2, 32.0f, c); }
;             } else {
; #pragma unroll
;                 for (int r = 0; r < 16; ++r) { p0[r] = 0.f; p1[r] = 0.f; }
;             }
; #pragma unroll
;             for (int ds = 0; ds < 4; ++ds) {
;                 const bf16x8 k0f = *(const LAS bf16x8*)(sb + koff + ds * 32);
;                 const bf16x8 k1f = *(const LAS bf16x8*)(sb + koff + 32 * KSTR + ds * 32);
;                 p0 = MFMA32(k0f, qf[ds], p0); p1 = MFMA32(k1f, qf[ds], p1);
;             }
;             const bool diag = (MODE == 0) ? (k0 + 63 > tw0) : (k0 + 63 >= tw0);
;             bf16x8 pf0, pf1, pf2, pf3;
;             if (MODE == 0) {
;                 if (diag) {
; #pragma unroll
;                     for (int r = 0; r < 16; ++r) { const int key = k0 + crow(r, hi); if (key > t) p0[r] = -INFINITY; if (key + 32 > t) p1[r] = -INFINITY; }
;                 }
.Lst_skip1:
	v_sub_u32_e64 v0, s89, 2 clamp
	v_lshlrev_b64 v[80:81], 18, v[0:1]
	v_lshl_add_u64 v[80:81], v[146:147], 0, v[80:81]
	v_lshlrev_b32_e32 v0, 7, v0
	global_load_dwordx4 v[128:131], v[80:81], off offset:1024
	v_lshl_add_u64 v[80:81], v[148:149], 0, v[0:1]
	v_add_co_u32_e32 v82, vcc, 0x100000, v80
	s_lshl_b32 s8, s89, 6
	s_nop 0
	v_addc_co_u32_e32 v83, vcc, 0, v81, vcc
	global_load_dwordx4 v[132:135], v[80:81], off
	global_load_dwordx4 v[136:139], v[82:83], off
	s_cmp_gt_i32 s8, s91
	s_cselect_b64 s[48:49], -1, 0
	s_or_b64 s[48:49], s[48:49], s[58:59]
	s_and_b64 vcc, exec, s[48:49]
	s_cbranch_vccnz .LBB0_428
	v_add_u32_e32 v0, s8, v166
	v_cvt_f32_i32_e32 v0, v0
	v_mov_b32_e32 v143, v142
	s_or_b32 s3, s8, 63
	s_cmp_le_i32 s3, s88
	v_fma_f32 v0, v142, v0, -v14
	v_fma_f32 v80, 0, v142, v0
	v_add_f32_e32 v81, v142, v0
	v_fma_f32 v82, v152, s12, v0
	v_fma_f32 v83, v153, s13, v0
	v_fma_f32 v84, v152, s14, v0
	v_fma_f32 v85, v153, s15, v0
	v_fma_f32 v86, v152, s16, v0
	v_fma_f32 v87, v153, s17, v0
	v_fma_f32 v88, v152, s18, v0
	v_fma_f32 v89, v153, s19, v0
	v_fma_f32 v90, v152, s20, v0
	v_fma_f32 v91, v153, s21, v0
	v_fma_f32 v92, v152, s22, v0
	v_fma_f32 v93, v153, s23, v0
	v_fma_f32 v94, v152, s24, v0
	v_fma_f32 v95, v153, s25, v0
	v_add_u32_e32 v0, 0, v163
	ds_read_b128 v[170:173], v0 offset:27648
	ds_read_b128 v[174:177], v0 offset:27680
	v_fma_f32 v110, v142, s28, v94
	v_fma_f32 v111, v143, s28, v95
	v_fma_f32 v108, v142, s28, v92
	v_fma_f32 v109, v143, s28, v93
	v_fma_f32 v106, v142, s28, v90
	v_fma_f32 v107, v143, s28, v91
	v_fma_f32 v104, v142, s28, v88
	v_fma_f32 v105, v143, s28, v89
	v_fma_f32 v102, v142, s28, v86
	v_fma_f32 v103, v143, s28, v87
	v_fma_f32 v100, v142, s28, v84
	v_fma_f32 v101, v143, s28, v85
	v_fma_f32 v98, v142, s28, v82
	v_fma_f32 v99, v143, s28, v83
	v_fma_f32 v96, v154, s28, v80
	v_fma_f32 v97, v155, s28, v81
	s_waitcnt lgkmcnt(1)
	v_mfma_f32_32x32x16_bf16 v[80:95], v[170:173], v[112:115], v[80:95]
	ds_read_b128 v[170:173], v0 offset:32256
	ds_read_b128 v[178:181], v0 offset:32288
	s_waitcnt lgkmcnt(1)
	v_mfma_f32_32x32x16_bf16 v[96:111], v[170:173], v[112:115], v[96:111]
	v_mfma_f32_32x32x16_bf16 v[80:95], v[174:177], v[116:119], v[80:95]
	ds_read_b128 v[170:173], v0 offset:27712
	ds_read_b128 v[174:177], v0 offset:27744
	s_waitcnt lgkmcnt(2)
	v_mfma_f32_32x32x16_bf16 v[96:111], v[178:181], v[116:119], v[96:111]
	s_waitcnt lgkmcnt(1)
	v_mfma_f32_32x32x16_bf16 v[80:95], v[170:173], v[120:123], v[80:95]
	ds_read_b128 v[170:173], v0 offset:32320
	ds_read_b128 v[178:181], v0 offset:32352
	s_waitcnt lgkmcnt(1)
	v_mfma_f32_32x32x16_bf16 v[96:111], v[170:173], v[120:123], v[96:111]
	v_mfma_f32_32x32x16_bf16 v[80:95], v[174:177], v[124:127], v[80:95]
	s_waitcnt lgkmcnt(0)
	v_mfma_f32_32x32x16_bf16 v[96:111], v[178:181], v[124:127], v[96:111]
	s_cbranch_scc1 .LBB0_420
	v_or_b32_e32 v15, s8, v165
	v_or_b32_e32 v143, 32, v15
	v_cmp_le_i32_e32 vcc, v143, v140
	v_or_b32_e32 v143, 33, v15
	s_nop 6
	v_cndmask_b32_e32 v96, v159, v96, vcc
	v_cmp_lt_i32_e32 vcc, v15, v140
	s_nop 1
	v_cndmask_b32_e32 v81, v159, v81, vcc
	v_cmp_le_i32_e32 vcc, v15, v140
	s_nop 1
	v_cndmask_b32_e32 v80, v159, v80, vcc
	v_cmp_le_i32_e32 vcc, v143, v140
	v_or_b32_e32 v143, 2, v15
	s_nop 0
	v_cndmask_b32_e32 v97, v159, v97, vcc
	v_cmp_le_i32_e32 vcc, v143, v140
	v_or_b32_e32 v143, 34, v15
	s_nop 0
	v_cndmask_b32_e32 v82, v159, v82, vcc
	v_cmp_le_i32_e32 vcc, v143, v140
	v_or_b32_e32 v143, 3, v15
	s_nop 0
	v_cndmask_b32_e32 v98, v159, v98, vcc
	v_cmp_le_i32_e32 vcc, v143, v140
	v_or_b32_e32 v143, 35, v15
	s_nop 0
	v_cndmask_b32_e32 v83, v159, v83, vcc
	v_cmp_le_i32_e32 vcc, v143, v140
	v_or_b32_e32 v143, 8, v15
	s_nop 0
	v_cndmask_b32_e32 v99, v159, v99, vcc
	v_cmp_le_i32_e32 vcc, v143, v140
	v_or_b32_e32 v143, 40, v15
	s_nop 0
	v_cndmask_b32_e32 v84, v159, v84, vcc
	v_cmp_le_i32_e32 vcc, v143, v140
	v_or_b32_e32 v143, 9, v15
	s_nop 0
	v_cndmask_b32_e32 v100, v159, v100, vcc
	v_cmp_le_i32_e32 vcc, v143, v140
	v_or_b32_e32 v143, 41, v15
	s_nop 0
	v_cndmask_b32_e32 v85, v159, v85, vcc
	v_cmp_le_i32_e32 vcc, v143, v140
	v_or_b32_e32 v143, 10, v15
	s_nop 0
	v_cndmask_b32_e32 v101, v159, v101, vcc
	v_cmp_le_i32_e32 vcc, v143, v140
	v_or_b32_e32 v143, 42, v15
	s_nop 0
	v_cndmask_b32_e32 v86, v159, v86, vcc
	v_cmp_le_i32_e32 vcc, v143, v140
	v_or_b32_e32 v143, 11, v15
	s_nop 0
	v_cndmask_b32_e32 v102, v159, v102, vcc
	v_cmp_le_i32_e32 vcc, v143, v140
	v_or_b32_e32 v143, 43, v15
	s_nop 0
	v_cndmask_b32_e32 v87, v159, v87, vcc
	v_cmp_le_i32_e32 vcc, v143, v140
	v_or_b32_e32 v143, 16, v15
	s_nop 0
	v_cndmask_b32_e32 v103, v159, v103, vcc
	v_cmp_le_i32_e32 vcc, v143, v140
	v_or_b32_e32 v143, 48, v15
	s_nop 0
	v_cndmask_b32_e32 v88, v159, v88, vcc
	v_cmp_le_i32_e32 vcc, v143, v140
	v_or_b32_e32 v143, 17, v15
	s_nop 0
	v_cndmask_b32_e32 v104, v159, v104, vcc
	v_cmp_le_i32_e32 vcc, v143, v140
	v_or_b32_e32 v143, 49, v15
	s_nop 0
	v_cndmask_b32_e32 v89, v159, v89, vcc
	v_cmp_le_i32_e32 vcc, v143, v140
	v_or_b32_e32 v143, 18, v15
	s_nop 0
	v_cndmask_b32_e32 v105, v159, v105, vcc
	v_cmp_le_i32_e32 vcc, v143, v140
	v_or_b32_e32 v143, 50, v15
	s_nop 0
	v_cndmask_b32_e32 v90, v159, v90, vcc
	v_cmp_le_i32_e32 vcc, v143, v140
	v_or_b32_e32 v143, 19, v15
	s_nop 0
	v_cndmask_b32_e32 v106, v159, v106, vcc
	v_cmp_le_i32_e32 vcc, v143, v140
	v_or_b32_e32 v143, 51, v15
	s_nop 0
	v_cndmask_b32_e32 v91, v159, v91, vcc
	v_cmp_le_i32_e32 vcc, v143, v140
	v_or_b32_e32 v143, 24, v15
	s_nop 0
	v_cndmask_b32_e32 v107, v159, v107, vcc
	v_cmp_le_i32_e32 vcc, v143, v140
	v_or_b32_e32 v143, 56, v15
	s_nop 0
	v_cndmask_b32_e32 v92, v159, v92, vcc
	v_cmp_le_i32_e32 vcc, v143, v140
	v_or_b32_e32 v143, 25, v15
	s_nop 0
	v_cndmask_b32_e32 v108, v159, v108, vcc
	v_cmp_le_i32_e32 vcc, v143, v140
	v_or_b32_e32 v143, 57, v15
	s_nop 0
	v_cndmask_b32_e32 v93, v159, v93, vcc
	v_cmp_le_i32_e32 vcc, v143, v140
	v_or_b32_e32 v143, 26, v15
	s_nop 0
	v_cndmask_b32_e32 v109, v159, v109, vcc
	v_cmp_le_i32_e32 vcc, v143, v140
	v_or_b32_e32 v143, 58, v15
	s_nop 0
	v_cndmask_b32_e32 v94, v159, v94, vcc
	v_cmp_le_i32_e32 vcc, v143, v140
	v_or_b32_e32 v143, 27, v15
	v_or_b32_e32 v15, 59, v15
	v_cndmask_b32_e32 v110, v159, v110, vcc
	v_cmp_le_i32_e32 vcc, v143, v140
	s_nop 1
	v_cndmask_b32_e32 v95, v159, v95, vcc
	v_cmp_le_i32_e32 vcc, v15, v140
	s_nop 1
	v_cndmask_b32_e32 v111, v159, v111, vcc
